# phase-0 w_fourier@w_out fold: 4 outputs per thread in one pass (48 loads in flight)
# baseline (speedup 1.0000x reference)
; __device__ __forceinline__ unsigned f2bf(float f) { unsigned u = __builtin_bit_cast(unsigned, f); return (u + 0x7fffu + ((u >> 16) & 1u)) >> 16; }
; template <int PH> __device__ __forceinline__ void phase_body(const Args& args, LAS unsigned char* lds) {
;     ...
;             for (int i = gt; i < 2 * 256 * 1024; i += NGT) { const int l = i / (256 * 1024), r = i % (256 * 1024), kp = r / 1024, n = r % 1024;
;                 const float* wf = w_fou + (size_t)l * 256 * 256 + kp * 256; const float* wo = w_out + (size_t)l * DM * DM + (size_t)768 * DM + n; float s = 0.f;
;                 for (int j = 0; j < 256; ++j) s = fmaf(wf[j], wo[(size_t)j * DM], s);
;                 WOUT[(size_t)l * DM * DM + (size_t)n * DM + 768 + kp] = (bf16_t)f2bf(s); }
.LBB0_40:
	s_or_b64 exec, exec, s[4:5]
	s_mov_b32 s4, 0x80000
	v_cmp_gt_i32_e32 vcc, s4, v2
	s_and_saveexec_b64 s[4:5], vcc
	s_cbranch_execz .LBB0_45
	s_load_dwordx16 s[52:67], s[0:1], 0x40
	s_mov_b64 s[12:13], 0
	s_mov_b32 s20, 0x309000
	s_mov_b32 s21, 0x30b000
	s_mov_b32 s22, 0x30d000
	s_waitcnt lgkmcnt(0)
	s_mov_b64 s[16:17], s[64:65]
	s_mov_b64 s[18:19], s[66:67]
	s_add_u32 s6, s18, 60
	s_addc_u32 s7, s19, 0
	s_mov_b32 s16, 0x301000
	s_mov_b32 s17, 0x303000
	s_mov_b32 s18, 0x305000
	s_mov_b32 s19, 0x307000
	s_mov_b32 s24, 0x30e000
	s_movk_i32 s33, 0x7fff
	s_mov_b32 s35, 0x7ffff
	s_cmp_lg_u32 s34, 0x20000
	s_cbranch_scc1 .Lfold_orig
	s_load_dwordx8 s[52:59], s[0:1], 0x80
	v_lshrrev_b32_e32 v100, 10, v2
	v_and_b32_e32 v101, 0x3ff, v2
	v_lshlrev_b32_e32 v120, 2, v101
	v_add_u32_e32 v121, 0x1000, v120
	v_add_u32_e32 v122, 0x2000, v120
	v_add_u32_e32 v123, 0x3000, v120
	v_add_u32_e32 v124, 0x4000, v120
	v_add_u32_e32 v125, 0x5000, v120
	v_add_u32_e32 v126, 0x6000, v120
	v_add_u32_e32 v127, 0x7000, v120
	v_add_u32_e32 v128, 0x8000, v120
	v_add_u32_e32 v129, 0x9000, v120
	v_add_u32_e32 v130, 0xa000, v120
	v_add_u32_e32 v131, 0xb000, v120
	v_add_u32_e32 v132, 0xc000, v120
	v_add_u32_e32 v133, 0xd000, v120
	v_add_u32_e32 v134, 0xe000, v120
	v_add_u32_e32 v135, 0xf000, v120
	v_lshlrev_b32_e32 v136, 10, v100
	v_add_u32_e32 v137, 0x20000, v136
	v_add_u32_e32 v138, 0x40000, v136
	v_add_u32_e32 v139, 0x60000, v136
	v_mov_b32_e32 v116, 0
	v_mov_b32_e32 v117, 0
	v_mov_b32_e32 v118, 0
	v_mov_b32_e32 v119, 0
	s_waitcnt lgkmcnt(0)
	s_add_u32 s54, s52, 0x300000
	s_addc_u32 s55, s53, 0
	s_add_u32 s56, s54, 0x400000
	s_addc_u32 s57, s55, 0
	s_add_u32 s58, s6, 0xffffffc4
	s_addc_u32 s59, s7, -1
	s_mov_b32 s14, 0
.Lfold_loop:
	global_load_dwordx4 v[152:155], v136, s[58:59]
	global_load_dwordx4 v[156:159], v136, s[58:59] offset:16
	global_load_dwordx4 v[160:163], v136, s[58:59] offset:32
	global_load_dwordx4 v[164:167], v136, s[58:59] offset:48
	global_load_dwordx4 v[168:171], v137, s[58:59]
	global_load_dwordx4 v[172:175], v137, s[58:59] offset:16
	global_load_dwordx4 v[176:179], v137, s[58:59] offset:32
	global_load_dwordx4 v[180:183], v137, s[58:59] offset:48
	global_load_dwordx4 v[184:187], v138, s[58:59]
	global_load_dwordx4 v[188:191], v138, s[58:59] offset:16
	global_load_dwordx4 v[192:195], v138, s[58:59] offset:32
	global_load_dwordx4 v[196:199], v138, s[58:59] offset:48
	global_load_dwordx4 v[200:203], v139, s[58:59]
	global_load_dwordx4 v[204:207], v139, s[58:59] offset:16
	global_load_dwordx4 v[208:211], v139, s[58:59] offset:32
	global_load_dwordx4 v[212:215], v139, s[58:59] offset:48
	global_load_dword v216, v120, s[54:55]
	global_load_dword v217, v121, s[54:55]
	global_load_dword v218, v122, s[54:55]
	global_load_dword v219, v123, s[54:55]
	global_load_dword v220, v124, s[54:55]
	global_load_dword v221, v125, s[54:55]
	global_load_dword v222, v126, s[54:55]
	global_load_dword v223, v127, s[54:55]
	global_load_dword v224, v128, s[54:55]
	global_load_dword v225, v129, s[54:55]
	global_load_dword v226, v130, s[54:55]
	global_load_dword v227, v131, s[54:55]
	global_load_dword v228, v132, s[54:55]
	global_load_dword v229, v133, s[54:55]
	global_load_dword v230, v134, s[54:55]
	global_load_dword v231, v135, s[54:55]
	global_load_dword v232, v120, s[56:57]
	global_load_dword v233, v121, s[56:57]
	global_load_dword v234, v122, s[56:57]
	global_load_dword v235, v123, s[56:57]
	global_load_dword v236, v124, s[56:57]
	global_load_dword v237, v125, s[56:57]
	global_load_dword v238, v126, s[56:57]
	global_load_dword v239, v127, s[56:57]
	global_load_dword v240, v128, s[56:57]
	global_load_dword v241, v129, s[56:57]
	global_load_dword v242, v130, s[56:57]
	global_load_dword v243, v131, s[56:57]
	global_load_dword v244, v132, s[56:57]
	global_load_dword v245, v133, s[56:57]
	global_load_dword v246, v134, s[56:57]
	global_load_dword v247, v135, s[56:57]
	s_add_u32 s54, s54, 0x10000
	s_addc_u32 s55, s55, 0
	s_add_u32 s56, s56, 0x10000
	s_addc_u32 s57, s57, 0
	s_add_u32 s58, s58, 64
	s_addc_u32 s59, s59, 0
	s_add_i32 s14, s14, 1
	s_waitcnt vmcnt(0)
	v_fmac_f32_e32 v116, v152, v216
	v_fmac_f32_e32 v117, v168, v216
	v_fmac_f32_e32 v118, v184, v232
	v_fmac_f32_e32 v119, v200, v232
	v_fmac_f32_e32 v116, v153, v217
	v_fmac_f32_e32 v117, v169, v217
	v_fmac_f32_e32 v118, v185, v233
	v_fmac_f32_e32 v119, v201, v233
	v_fmac_f32_e32 v116, v154, v218
	v_fmac_f32_e32 v117, v170, v218
	v_fmac_f32_e32 v118, v186, v234
	v_fmac_f32_e32 v119, v202, v234
	v_fmac_f32_e32 v116, v155, v219
	v_fmac_f32_e32 v117, v171, v219
	v_fmac_f32_e32 v118, v187, v235
	v_fmac_f32_e32 v119, v203, v235
	v_fmac_f32_e32 v116, v156, v220
	v_fmac_f32_e32 v117, v172, v220
	v_fmac_f32_e32 v118, v188, v236
	v_fmac_f32_e32 v119, v204, v236
	v_fmac_f32_e32 v116, v157, v221
	v_fmac_f32_e32 v117, v173, v221
	v_fmac_f32_e32 v118, v189, v237
	v_fmac_f32_e32 v119, v205, v237
	v_fmac_f32_e32 v116, v158, v222
	v_fmac_f32_e32 v117, v174, v222
	v_fmac_f32_e32 v118, v190, v238
	v_fmac_f32_e32 v119, v206, v238
	v_fmac_f32_e32 v116, v159, v223
	v_fmac_f32_e32 v117, v175, v223
	v_fmac_f32_e32 v118, v191, v239
	v_fmac_f32_e32 v119, v207, v239
	v_fmac_f32_e32 v116, v160, v224
	v_fmac_f32_e32 v117, v176, v224
	v_fmac_f32_e32 v118, v192, v240
	v_fmac_f32_e32 v119, v208, v240
	v_fmac_f32_e32 v116, v161, v225
	v_fmac_f32_e32 v117, v177, v225
	v_fmac_f32_e32 v118, v193, v241
	v_fmac_f32_e32 v119, v209, v241
	v_fmac_f32_e32 v116, v162, v226
	v_fmac_f32_e32 v117, v178, v226
	v_fmac_f32_e32 v118, v194, v242
	v_fmac_f32_e32 v119, v210, v242
	v_fmac_f32_e32 v116, v163, v227
	v_fmac_f32_e32 v117, v179, v227
	v_fmac_f32_e32 v118, v195, v243
	v_fmac_f32_e32 v119, v211, v243
	v_fmac_f32_e32 v116, v164, v228
	v_fmac_f32_e32 v117, v180, v228
	v_fmac_f32_e32 v118, v196, v244
	v_fmac_f32_e32 v119, v212, v244
	v_fmac_f32_e32 v116, v165, v229
	v_fmac_f32_e32 v117, v181, v229
	v_fmac_f32_e32 v118, v197, v245
	v_fmac_f32_e32 v119, v213, v245
	v_fmac_f32_e32 v116, v166, v230
	v_fmac_f32_e32 v117, v182, v230
	v_fmac_f32_e32 v118, v198, v246
	v_fmac_f32_e32 v119, v214, v246
	v_fmac_f32_e32 v116, v167, v231
	v_fmac_f32_e32 v117, v183, v231
	v_fmac_f32_e32 v118, v199, v247
	v_fmac_f32_e32 v119, v215, v247
	s_cmp_lg_u32 s14, 16
	s_cbranch_scc1 .Lfold_loop
	v_lshlrev_b32_e32 v102, 11, v101
	v_lshl_add_u32 v102, v100, 1, v102
	v_add_u32_e32 v103, 0x200000, v102
	v_bfe_u32 v104, v116, 16, 1
	v_add3_u32 v116, v116, v104, s33
	global_store_short_d16_hi v102, v116, s[2:3] offset:1536
	v_bfe_u32 v104, v117, 16, 1
	v_add3_u32 v117, v117, v104, s33
	global_store_short_d16_hi v102, v117, s[2:3] offset:1792
	v_bfe_u32 v104, v118, 16, 1
	v_add3_u32 v118, v118, v104, s33
	global_store_short_d16_hi v103, v118, s[2:3] offset:1536
	v_bfe_u32 v104, v119, 16, 1
	v_add3_u32 v119, v119, v104, s33
	global_store_short_d16_hi v103, v119, s[2:3] offset:1792
	s_load_dwordx8 s[52:59], s[0:1], 0x80
	s_waitcnt lgkmcnt(0)
	s_branch .LBB0_45
.Lfold_orig:
	v_mov_b32_e32 v1, v2
